# SEAM(0): cooperative-groups grid sync replaced by a flat counter barrier on spare barrier words (flag + arrival counter, bounded spins)
# speedup vs baseline: 1.0054x; 1.0054x over previous
; #define LAS __attribute__((address_space(3)))
; __global__ void __launch_bounds__(NTHR, 2) fwd(Args args) {
;     extern __shared__ __attribute__((aligned(16))) unsigned char lds_raw[];
;     Frame F;
;     F.lds = (LAS unsigned char*)lds_raw;
;     F.tid = threadIdx.x; F.lane = F.tid & 63; F.wave = __builtin_amdgcn_readfirstlane(F.tid >> 6);
;     F.G = gridDim.x; F.bid = blockIdx.x;
; #pragma unroll
;     for (int i = 0; i < 12; ++i) F.in[i] = args.in[i];
;     F.out = args.out; F.ws = args.ws;
;     unsigned char* ws = args.ws;
;     bf16* XB = (bf16*)(ws + WS_XB); bf16* BIG = (bf16*)(ws + WS_BIG);
;     const bf16* WIN = (const bf16*)(ws + WS_WIN); const bf16* WOUT = (const bf16*)(ws + WS_WOUT);
;     const bf16* W1 = (const bf16*)(ws + WS_W1); const bf16* W2 = (const bf16*)(ws + WS_W2);
;     const int lo = args.ph_lo, hi = args.ph_hi;
;     ...
;     volatile LAS unsigned* MISC = (volatile LAS unsigned*)(F.lds + 131072 + 64);
;     unsigned* barw = (unsigned*)ws;
;     if (F.tid < 4) MISC[F.tid] = 0u;
;     if (lo == 0 && F.bid == 0) for (int i = F.tid; i < XCD_BAR_WORDS; i += NTHR) barw[i] = 0u;
;     __syncthreads();
;     XcdBarrier bar; bar.bar = barw; bar.x = 0; bar.st = MISC;
_Z3fwd4Args:
	s_mov_b32 s98, 1
	v_writelane_b32 v229, s98, 52
	s_load_dword s18, s[0:1], 0x78
	s_load_dwordx8 s[88:95], s[0:1], 0x40
	s_load_dwordx4 s[20:23], s[0:1], 0x60
	s_load_dwordx2 s[80:81], s[0:1], 0x70
	s_add_u32 s4, s0, 0x78
	v_and_b32_e32 v146, 0x3ff, v0
	s_addc_u32 s5, s1, 0
	s_mov_b32 s84, s2
	v_readfirstlane_b32 s3, v146
	v_writelane_b32 v231, s4, 0
	v_cmp_gt_u32_e32 vcc, 4, v146
	s_nop 0
	v_writelane_b32 v231, s5, 1
	s_and_saveexec_b64 s[4:5], vcc
	v_lshl_add_u32 v1, v146, 2, 0
	v_add_u32_e32 v1, 0x20040, v1
	v_mov_b32_e32 v2, 0
	ds_write_b32 v1, v2
	s_or_b64 exec, exec, s[4:5]
	s_load_dwordx16 s[36:51], s[0:1], 0x0
	s_waitcnt lgkmcnt(0)
	s_or_b32 s0, s80, s84
	s_cmp_lg_u32 s0, 0
	s_mov_b32 s4, 0
	v_writelane_b32 v231, s36, 2
	s_nop 1
	v_writelane_b32 v231, s37, 3
	v_writelane_b32 v231, s38, 4
	v_writelane_b32 v231, s39, 5
	v_writelane_b32 v231, s40, 6
	v_writelane_b32 v231, s41, 7
	v_writelane_b32 v231, s42, 8
	v_writelane_b32 v231, s43, 9
	v_writelane_b32 v231, s44, 10
	v_writelane_b32 v231, s45, 11
	v_writelane_b32 v231, s46, 12
	v_writelane_b32 v231, s47, 13
	v_writelane_b32 v231, s48, 14
	v_writelane_b32 v231, s49, 15
	v_writelane_b32 v231, s50, 16
	v_writelane_b32 v231, s51, 17
	s_cbranch_scc1 .LBB0_10
	v_sub_u32_e32 v1, 0xd7f, v146
	v_lshrrev_b32_e32 v2, 9, v1
	v_add_u32_e32 v1, 2, v2
	v_add_u32_e32 v147, 0x200, v146
	v_and_b32_e32 v3, 14, v1
	v_mov_b32_e32 v1, v2
	s_mov_b64 s[6:7], 0
	s_mov_b32 s5, 1
	v_mov_b32_e32 v5, 0
	s_mov_b32 s8, s4
	v_mov_b64_e32 v[6:7], v[146:147]
	s_branch .LBB0_5

; #define REPS(k) for (int _rep = 0; _rep < ((PROBE_PHASE) == (k) ? 2 : 1); ++_rep)
; #define LAS __attribute__((address_space(3)))
; __device__ __forceinline__ unsigned xb_add(unsigned* p, unsigned v) { return __hip_atomic_fetch_add(p, v, __ATOMIC_RELAXED, __HIP_MEMORY_SCOPE_AGENT); }
; __device__ __forceinline__ unsigned xb_xcc_id() { return (unsigned)__builtin_amdgcn_s_getreg((3 << 11) | 20) & 0xFu; }
; #define SEAM(k) do { if (IN(k) && IN((k) + 1)) { if ((k) == 0) { cg::this_grid().sync(); bar = xcd_barrier_post(barw, MISC); } else { xcd_barrier(bar); } } } while (0)
; __device__ __forceinline__ XcdBarrier xcd_barrier_post(unsigned* bar, volatile LAS unsigned* st) {
;     XcdBarrier b; b.bar = bar; b.x = xb_xcc_id(); b.st = st;
;     if (threadIdx.x == 0) (void)xb_add(&bar[XB_XCNT(b.x)], 1u);
;     return b;
; }
; __global__ void __launch_bounds__(NTHR, 2) fwd(Args args) {
;     ...
;     volatile LAS unsigned* MISC = (volatile LAS unsigned*)(F.lds + 131072 + 64);
;     unsigned* barw = (unsigned*)ws;
;     if (F.tid < 4) MISC[F.tid] = 0u;
;     if (lo == 0 && F.bid == 0) for (int i = F.tid; i < XCD_BAR_WORDS; i += NTHR) barw[i] = 0u;
;     __syncthreads();
;     XcdBarrier bar; bar.bar = barw; bar.x = 0; bar.st = MISC;
;     if (IN(0)) REPS(0) { prep_weights(F, 0); prep_misc(F); } SEAM(0);
.LBB0_114:
	s_cmp_gt_i32 s81, 1
	s_cselect_b64 s[4:5], -1, 0
	s_and_b64 s[0:1], s[0:1], s[4:5]
	s_andn2_b64 vcc, exec, s[0:1]
	s_mov_b32 s0, 0
	v_writelane_b32 v231, s0, 24
	s_cbranch_vccnz .LBB0_129
	s_waitcnt vmcnt(0) lgkmcnt(0)
	s_barrier
	v_readfirstlane_b32 s98, v146
	s_or_b32 s99, s98, s84
	v_writelane_b32 v229, s99, 52
	v_writelane_b32 v229, s22, 55
	v_writelane_b32 v229, s23, 54
	s_cmp_lg_u32 s98, 0
	s_cbranch_scc1 .Lg0_done
	s_mov_b64 s[0:1], exec
	s_mov_b64 exec, 1
	buffer_wbl2 sc1
	s_waitcnt vmcnt(0)
	v_mov_b32_e32 v2, 0
	s_cmp_lg_u32 s84, 0
	s_cbranch_scc1 .Lg0_wait
	v_mov_b32_e32 v0, 0x5ea0b001
	global_atomic_add v2, v0, s[22:23]
	s_waitcnt vmcnt(0)
.Lg0_wait:
	s_movk_i32 s98, 0x400
.Lg0_wl:
	global_load_dword v0, v2, s[22:23] sc1
	s_waitcnt vmcnt(0)
	v_readfirstlane_b32 s99, v0
	s_cmp_eq_u32 s99, 0x5ea0b001
	s_cbranch_scc1 .Lg0_arrive
	s_sleep 1
	s_add_i32 s98, s98, -1
	s_cmp_lg_u32 s98, 0
	s_cbranch_scc1 .Lg0_wl
.Lg0_arrive:
	v_mov_b32_e32 v0, 1
	global_atomic_add v2, v0, s[22:23] offset:256
	s_movk_i32 s98, 0x400
.Lg0_sl:
	global_load_dword v0, v2, s[22:23] offset:256 sc1
	s_waitcnt vmcnt(0)
	v_readfirstlane_b32 s99, v0
	s_cmp_ge_u32 s99, s18
	s_cbranch_scc1 .Lg0_rel
	s_sleep 1
	s_add_i32 s98, s98, -1
	s_cmp_lg_u32 s98, 0
	s_cbranch_scc1 .Lg0_sl
.Lg0_rel:
	buffer_inv sc1
	s_waitcnt vmcnt(0)
	s_mov_b64 exec, s[0:1]
.Lg0_done:
	s_barrier
	s_getreg_b32 s0, hwreg(HW_REG_XCC_ID, 0, 4)
	s_and_b32 s0, s0, 15
	v_cmp_eq_u32_e32 vcc, 0, v146
	v_writelane_b32 v231, s0, 24
	s_and_saveexec_b64 s[0:1], vcc
	s_cbranch_execz .LBB0_128
	s_mov_b64 s[6:7], exec
	v_mbcnt_lo_u32_b32 v0, s6, 0
	v_mbcnt_hi_u32_b32 v0, s7, v0
	v_cmp_eq_u32_e32 vcc, 0, v0
	s_and_b64 s[8:9], exec, vcc
	s_mov_b64 exec, s[8:9]
	s_cbranch_execz .LBB0_128
	v_readlane_b32 s2, v231, 24
	s_lshl_b32 s3, s2, 8
	s_bcnt1_i32_b64 s6, s[6:7]
	v_mov_b32_e32 v0, s3
	v_mov_b32_e32 v1, s6
	global_atomic_add v0, v1, s[22:23] offset:1024

; __global__ void __launch_bounds__(NTHR, 2) fwd(Args args) {
;     ...
;     if (IN(16)) { phase_ln(F, F.in[10] + DM, F.in[11] + DM, false); }
;     ...
; }
.LBB0_1532:
	v_readlane_b32 s98, v229, 52
	v_readlane_b32 s100, v229, 55
	v_readlane_b32 s101, v229, 54
	s_nop 4
	s_cmp_lg_u32 s98, 0
	s_cbranch_scc1 .Lg0_end
	s_mov_b64 exec, 1
	v_mov_b32_e32 v2, 0
	v_mov_b32_e32 v0, 0x5ea0b001
	s_nop 4
	global_atomic_sub v2, v0, s[100:101]
	s_waitcnt vmcnt(0)
